# v037 + NA: removed dead v[130:145] negm copies (8 v_mov_b64 per step), B-step QK reads C from the primary negm tuple
# speedup vs baseline: 1.0038x; 1.0038x over previous
; __device__ __forceinline__ float max3f(float a, float b, float c) { float r; asm("v_max3_f32 %0, %1, %2, %3" : "=v"(r) : "v"(a), "v"(b), "v"(c)); return r; }
; __device__ __forceinline__ float rowmax32(const f32x16& p0, const f32x16& p1) {
;     float a = max3f(p0[0], p0[1], p1[0]), b = max3f(p0[2], p0[3], p1[1]); a = max3f(a, p1[2], p1[3]);
; #pragma unroll
;     for (int r = 4; r < 16; r += 4) { a = max3f(a, p0[r], p0[r + 1]); b = max3f(b, p0[r + 2], p0[r + 3]); a = max3f(a, p1[r], p1[r + 1]); b = max3f(b, p1[r + 2], p1[r + 3]); }
;     const float m = fmaxf(a, b);
;     auto rr = __builtin_amdgcn_permlane32_swap(__float_as_uint(m), __float_as_uint(m), false, false);
;     return fmaxf(__uint_as_float(rr[0]), __uint_as_float(rr[1]));
; }
.LBB0_779:
.LBB0_780:
.LBB0_781:
.LBB0_782:
	s_add_i32 s87, s1, -4
	s_add_i32 s0, s74, -3
	s_cmp_ge_i32 s0, s33
	s_cselect_b64 s[94:95], -1, 0
	s_cmp_lt_i32 s0, s88
	s_cselect_b64 s[96:97], -1, 0
	s_and_b64 s[94:95], s[94:95], s[96:97]
	s_add_i32 s0, s1, -3
	s_cmp_lt_i32 s87, s81
	s_cselect_b64 s[96:97], -1, 0
	s_and_b64 vcc, s[94:95], s[96:97]
	s_andn2_b64 vcc, exec, vcc
	s_cbranch_vccnz .LBB0_817
	s_and_b32 s90, s0, 3
	s_mulk_i32 s90, 0x3400
	v_add_u32_e32 v0, s90, v173
	ds_read_b128 v[64:67], v0 offset:4608
	ds_read_b128 v[68:71], v0
	ds_read_b128 v[72:75], v0 offset:32
	ds_read_b128 v[220:223], v0 offset:4640
	ds_read_b128 v[224:227], v0 offset:64
	ds_read_b128 v[228:231], v0 offset:4672
	ds_read_b128 v[232:235], v0 offset:96
	ds_read_b128 v[236:239], v0 offset:4704
	s_waitcnt lgkmcnt(7)
	v_mfma_f32_32x32x16_bf16 v[96:111], v[64:67], v[146:149], v[112:127]
	s_waitcnt lgkmcnt(6)
	v_mfma_f32_32x32x16_bf16 v[130:145], v[68:71], v[146:149], v[112:127]
	s_waitcnt lgkmcnt(5)
	v_mfma_f32_32x32x16_bf16 v[130:145], v[72:75], v[150:153], v[130:145]
	s_waitcnt lgkmcnt(4)
	v_mfma_f32_32x32x16_bf16 v[96:111], v[220:223], v[150:153], v[96:111]
	s_waitcnt lgkmcnt(3)
	v_mfma_f32_32x32x16_bf16 v[130:145], v[224:227], v[154:157], v[130:145]
	s_waitcnt lgkmcnt(2)
	v_mfma_f32_32x32x16_bf16 v[96:111], v[228:231], v[154:157], v[96:111]
	s_waitcnt lgkmcnt(1)
	v_mfma_f32_32x32x16_bf16 v[130:145], v[232:235], v[158:161], v[130:145]
	s_waitcnt lgkmcnt(0)
	v_mfma_f32_32x32x16_bf16 v[96:111], v[236:239], v[158:161], v[96:111]
	ds_read_b32 v0, v179 offset:128
	ds_read_b32 v64, v179
	ds_read_b32 v65, v179 offset:4
	ds_read_b32 v66, v179 offset:8
	ds_read_b32 v67, v179 offset:12
	ds_read_b32 v68, v179 offset:32
	ds_read_b32 v69, v179 offset:36
	ds_read_b32 v70, v179 offset:40
	ds_read_b32 v71, v179 offset:44
	ds_read_b32 v72, v179 offset:64
	ds_read_b32 v73, v179 offset:68
	ds_read_b32 v74, v179 offset:72
	ds_read_b32 v75, v179 offset:76
	ds_read_b32 v76, v179 offset:96
	ds_read_b32 v77, v179 offset:100
	ds_read_b32 v78, v179 offset:104
	ds_read_b32 v79, v179 offset:108
	s_waitcnt lgkmcnt(0)
	v_add_f32_e32 v64, v130, v64
	v_cndmask_b32_e64 v64, v177, v64, s[6:7]
	v_add_f32_e32 v65, v131, v65
	v_cndmask_b32_e64 v65, v177, v65, s[10:11]
	v_add_f32_e32 v66, v132, v66
	v_cndmask_b32_e64 v66, v177, v66, s[14:15]
	v_add_f32_e32 v67, v133, v67
	v_cndmask_b32_e64 v67, v177, v67, s[18:19]
	v_add_f32_e32 v68, v134, v68
	v_cndmask_b32_e64 v68, v177, v68, s[22:23]
	v_add_f32_e32 v69, v135, v69
	v_cndmask_b32_e64 v69, v177, v69, s[26:27]
	v_add_f32_e32 v70, v136, v70
	v_cndmask_b32_e64 v70, v177, v70, s[30:31]
	v_add_f32_e32 v71, v137, v71
	v_cndmask_b32_e64 v71, v177, v71, s[36:37]
	v_add_f32_e32 v72, v138, v72
	v_cndmask_b32_e64 v72, v177, v72, s[40:41]
	v_add_f32_e32 v73, v139, v73
	v_cndmask_b32_e64 v73, v177, v73, s[44:45]
	v_add_f32_e32 v74, v140, v74
	v_cndmask_b32_e64 v74, v177, v74, s[48:49]
	v_add_f32_e32 v75, v141, v75
	v_cndmask_b32_e64 v75, v177, v75, s[52:53]
	v_add_f32_e32 v76, v142, v76
	v_cndmask_b32_e64 v76, v177, v76, s[56:57]
	v_add_f32_e32 v77, v143, v77
	v_cndmask_b32_e64 v77, v177, v77, s[60:61]
	v_add_f32_e32 v78, v144, v78
	v_cndmask_b32_e64 v78, v177, v78, s[64:65]
	v_add_f32_e32 v79, v145, v79
	v_cndmask_b32_e64 v79, v177, v79, s[68:69]
	ds_read_b32 v3, v179 offset:132
	ds_read_b32 v129, v179 offset:136
	ds_read_b32 v130, v179 offset:140
	ds_read_b32 v131, v179 offset:160
	ds_read_b32 v132, v179 offset:164
	ds_read_b32 v133, v179 offset:168
	ds_read_b32 v134, v179 offset:172
	ds_read_b32 v135, v179 offset:192
	ds_read_b32 v136, v179 offset:196
	ds_read_b32 v137, v179 offset:200
	ds_read_b32 v138, v179 offset:204
	ds_read_b32 v139, v179 offset:224
	ds_read_b32 v140, v179 offset:228
	ds_read_b32 v142, v179 offset:232
	ds_read_b32 v141, v179 offset:236
	s_waitcnt lgkmcnt(14)
	v_add_f32_e32 v0, v96, v0
	v_cndmask_b32_e64 v96, v177, v0, s[8:9]
	v_add_f32_e32 v0, v97, v3
	v_cndmask_b32_e64 v97, v177, v0, s[12:13]
	s_waitcnt lgkmcnt(13)
	v_add_f32_e32 v0, v98, v129
	v_cndmask_b32_e64 v98, v177, v0, s[16:17]
	s_waitcnt lgkmcnt(12)
	v_add_f32_e32 v0, v99, v130
	v_cndmask_b32_e64 v99, v177, v0, s[20:21]
	s_waitcnt lgkmcnt(11)
	v_add_f32_e32 v0, v100, v131
	v_cndmask_b32_e64 v100, v177, v0, s[24:25]
	s_waitcnt lgkmcnt(10)
	v_add_f32_e32 v0, v101, v132
	v_cndmask_b32_e64 v101, v177, v0, s[28:29]
	s_waitcnt lgkmcnt(9)
	v_add_f32_e32 v0, v102, v133
	v_cndmask_b32_e64 v102, v177, v0, s[34:35]
	s_waitcnt lgkmcnt(8)
	v_add_f32_e32 v0, v103, v134
	v_cndmask_b32_e64 v103, v177, v0, s[38:39]
	s_waitcnt lgkmcnt(7)
	v_add_f32_e32 v0, v104, v135
	v_cndmask_b32_e64 v104, v177, v0, s[42:43]
	s_waitcnt lgkmcnt(6)
	v_add_f32_e32 v0, v105, v136
	v_cndmask_b32_e64 v105, v177, v0, s[46:47]
	s_waitcnt lgkmcnt(5)
	v_add_f32_e32 v0, v106, v137
	v_cndmask_b32_e64 v106, v177, v0, s[50:51]
	s_waitcnt lgkmcnt(4)
	v_add_f32_e32 v0, v107, v138
	v_cndmask_b32_e64 v107, v177, v0, s[54:55]
	s_waitcnt lgkmcnt(3)
	v_add_f32_e32 v0, v108, v139
	v_cndmask_b32_e64 v108, v177, v0, s[58:59]
	s_waitcnt lgkmcnt(2)
	v_add_f32_e32 v0, v109, v140
	v_cndmask_b32_e64 v109, v177, v0, s[62:63]
	s_waitcnt lgkmcnt(1)
	v_add_f32_e32 v0, v110, v142
	v_cndmask_b32_e64 v110, v177, v0, s[66:67]
	s_waitcnt lgkmcnt(0)
	v_add_f32_e32 v0, v111, v141
	v_cndmask_b32_e64 v111, v177, v0, s[70:71]
	v_max3_f32 v0, v64, v65, v96
	v_max3_f32 v3, v66, v67, v97
	v_max3_f32 v0, v0, v98, v99
	v_max3_f32 v3, v3, v70, v71
	v_max3_f32 v0, v0, v68, v69
	v_max3_f32 v3, v3, v102, v103
	v_max3_f32 v0, v0, v100, v101
	v_max3_f32 v3, v3, v74, v75
	v_max3_f32 v0, v0, v72, v73
	v_max3_f32 v3, v3, v106, v107
	v_max3_f32 v0, v0, v104, v105
	v_max3_f32 v3, v3, v78, v79
	v_max3_f32 v0, v0, v76, v77
	v_max3_f32 v3, v3, v110, v111
	v_max3_f32 v0, v0, v108, v109
	v_max_f32_e32 v0, v0, v3
	v_mov_b32_e32 v3, v0
	s_nop 1
	v_permlane32_swap_b32_e32 v0, v3
	v_max_f32_e32 v3, v0, v3
	s_and_b64 vcc, exec, s[72:73]
	s_cbranch_vccz .LBB0_818

; __device__ __forceinline__ float max3f(float a, float b, float c) { float r; asm("v_max3_f32 %0, %1, %2, %3" : "=v"(r) : "v"(a), "v"(b), "v"(c)); return r; }
; __device__ __forceinline__ float rowmax32(const f32x16& p0, const f32x16& p1) {
;     float a = max3f(p0[0], p0[1], p1[0]), b = max3f(p0[2], p0[3], p1[1]); a = max3f(a, p1[2], p1[3]);
; #pragma unroll
;     for (int r = 4; r < 16; r += 4) { a = max3f(a, p0[r], p0[r + 1]); b = max3f(b, p0[r + 2], p0[r + 3]); a = max3f(a, p1[r], p1[r + 1]); b = max3f(b, p1[r + 2], p1[r + 3]); }
;     const float m = fmaxf(a, b);
;     auto rr = __builtin_amdgcn_permlane32_swap(__float_as_uint(m), __float_as_uint(m), false, false);
;     return fmaxf(__uint_as_float(rr[0]), __uint_as_float(rr[1]));
; }
.LBB0_829:
	s_add_i32 s74, s74, -2
	s_cmp_ge_i32 s74, s33
	s_cselect_b64 s[90:91], -1, 0
	s_cmp_lt_i32 s74, s88
	s_cselect_b64 s[94:95], -1, 0
	s_and_b64 s[90:91], s[90:91], s[94:95]
	s_cmp_le_i32 s85, s81
	s_cselect_b64 s[94:95], -1, 0
	s_and_b64 s[90:91], s[90:91], s[94:95]
	s_andn2_b64 vcc, exec, s[90:91]
	s_cbranch_vccnz .LBB0_863
	s_mulk_i32 s77, 0x3400
	v_add_u32_e32 v0, s77, v173
	ds_read_b128 v[4:7], v0 offset:4608
	ds_read_b128 v[8:11], v0
	ds_read_b128 v[12:15], v0 offset:32
	ds_read_b128 v[220:223], v0 offset:4640
	ds_read_b128 v[224:227], v0 offset:64
	ds_read_b128 v[228:231], v0 offset:4672
	ds_read_b128 v[232:235], v0 offset:96
	ds_read_b128 v[236:239], v0 offset:4704
	v_mov_b32_e32 v17, 0xff800000
	v_mov_b32_e32 v16, 0xff800000
	s_waitcnt lgkmcnt(6)
	v_mfma_f32_32x32x16_bf16 v[80:95], v[8:11], v[146:149], v[112:127]
	v_mfma_f32_32x32x16_bf16 v[130:145], v[4:7], v[146:149], v[112:127]
	s_waitcnt lgkmcnt(5)
	v_mfma_f32_32x32x16_bf16 v[80:95], v[12:15], v[150:153], v[80:95]
	s_waitcnt lgkmcnt(4)
	v_mfma_f32_32x32x16_bf16 v[130:145], v[220:223], v[150:153], v[130:145]
	s_waitcnt lgkmcnt(3)
	v_mfma_f32_32x32x16_bf16 v[80:95], v[224:227], v[154:157], v[80:95]
	s_waitcnt lgkmcnt(2)
	v_mfma_f32_32x32x16_bf16 v[130:145], v[228:231], v[154:157], v[130:145]
	s_waitcnt lgkmcnt(1)
	v_mfma_f32_32x32x16_bf16 v[80:95], v[232:235], v[158:161], v[80:95]
	s_waitcnt lgkmcnt(0)
	v_mfma_f32_32x32x16_bf16 v[130:145], v[236:239], v[158:161], v[130:145]
	ds_read_b32 v0, v179 offset:252
	ds_read_b32 v16, v179 offset:124
	ds_read_b32 v17, v179 offset:128
	ds_read_b32 v18, v179 offset:132
	ds_read_b32 v19, v179 offset:136
	ds_read_b32 v20, v179 offset:156
	ds_read_b32 v21, v179 offset:160
	ds_read_b32 v22, v179 offset:164
	ds_read_b32 v23, v179 offset:168
	ds_read_b32 v24, v179 offset:188
	ds_read_b32 v25, v179 offset:192
	ds_read_b32 v26, v179 offset:196
	ds_read_b32 v27, v179 offset:200
	ds_read_b32 v60, v179 offset:220
	ds_read_b32 v61, v179 offset:224
	ds_read_b32 v62, v179 offset:228
	ds_read_b32 v63, v179 offset:232
	s_waitcnt lgkmcnt(0)
	v_add_f32_e32 v16, v80, v16
	v_cndmask_b32_e64 v16, v177, v16, s[6:7]
	v_add_f32_e32 v17, v81, v17
	v_cndmask_b32_e64 v17, v177, v17, s[10:11]
	v_add_f32_e32 v18, v82, v18
	v_cndmask_b32_e64 v18, v177, v18, s[14:15]
	v_add_f32_e32 v19, v83, v19
	v_cndmask_b32_e64 v19, v177, v19, s[18:19]
	v_add_f32_e32 v20, v84, v20
	v_cndmask_b32_e64 v20, v177, v20, s[22:23]
	v_add_f32_e32 v21, v85, v21
	v_cndmask_b32_e64 v21, v177, v21, s[26:27]
	v_add_f32_e32 v22, v86, v22
	v_cndmask_b32_e64 v22, v177, v22, s[30:31]
	v_add_f32_e32 v23, v87, v23
	v_cndmask_b32_e64 v23, v177, v23, s[36:37]
	v_add_f32_e32 v24, v88, v24
	v_cndmask_b32_e64 v24, v177, v24, s[40:41]
	v_add_f32_e32 v25, v89, v25
	v_cndmask_b32_e64 v25, v177, v25, s[44:45]
	v_add_f32_e32 v26, v90, v26
	v_cndmask_b32_e64 v26, v177, v26, s[48:49]
	v_add_f32_e32 v27, v91, v27
	v_cndmask_b32_e64 v27, v177, v27, s[52:53]
	v_add_f32_e32 v60, v92, v60
	v_cndmask_b32_e64 v60, v177, v60, s[56:57]
	v_add_f32_e32 v61, v93, v61
	v_cndmask_b32_e64 v61, v177, v61, s[60:61]
	v_add_f32_e32 v62, v94, v62
	v_cndmask_b32_e64 v62, v177, v62, s[64:65]
	v_add_f32_e32 v63, v95, v63
	v_cndmask_b32_e64 v63, v177, v63, s[68:69]
	ds_read_b32 v4, v179 offset:256
	ds_read_b32 v5, v179 offset:260
	ds_read_b32 v6, v179 offset:264
	ds_read_b32 v7, v179 offset:284
	ds_read_b32 v8, v179 offset:288
	ds_read_b32 v9, v179 offset:292
	ds_read_b32 v10, v179 offset:296
	ds_read_b32 v11, v179 offset:316
	ds_read_b32 v12, v179 offset:320
	ds_read_b32 v13, v179 offset:324
	ds_read_b32 v14, v179 offset:328
	ds_read_b32 v15, v179 offset:348
	ds_read_b32 v80, v179 offset:352
	ds_read_b32 v82, v179 offset:356
	ds_read_b32 v81, v179 offset:360
	s_waitcnt lgkmcnt(14)
	v_add_f32_e32 v0, v130, v0
	v_add_f32_e32 v4, v131, v4
	s_waitcnt lgkmcnt(13)
	v_add_f32_e32 v5, v132, v5
	s_waitcnt lgkmcnt(12)
	v_add_f32_e32 v6, v133, v6
	s_waitcnt lgkmcnt(2)
	v_add_f32_e32 v87, v143, v80
	v_cndmask_b32_e64 v80, v177, v0, s[8:9]
	v_max3_f32 v0, v16, v17, v80
	s_waitcnt lgkmcnt(1)
	v_add_f32_e32 v94, v144, v82
	s_waitcnt lgkmcnt(0)
	v_add_f32_e32 v128, v145, v81
	v_cndmask_b32_e64 v82, v177, v5, s[16:17]
	v_cndmask_b32_e64 v81, v177, v6, s[20:21]
	v_max3_f32 v0, v0, v82, v81
	v_cndmask_b32_e64 v95, v177, v4, s[12:13]
	v_max3_f32 v4, v18, v19, v95
	v_add_f32_e32 v7, v134, v7
	v_add_f32_e32 v8, v135, v8
	v_add_f32_e32 v9, v136, v9
	v_add_f32_e32 v10, v137, v10
	v_max3_f32 v0, v0, v20, v21
	v_max3_f32 v4, v4, v22, v23
	v_cndmask_b32_e64 v84, v177, v7, s[24:25]
	v_cndmask_b32_e64 v89, v177, v8, s[28:29]
	v_max3_f32 v0, v0, v84, v89
	v_cndmask_b32_e64 v86, v177, v9, s[34:35]
	v_cndmask_b32_e64 v83, v177, v10, s[38:39]
	v_max3_f32 v4, v4, v86, v83
	v_add_f32_e32 v11, v138, v11
	v_add_f32_e32 v12, v139, v12
	v_add_f32_e32 v13, v140, v13
	v_add_f32_e32 v14, v141, v14
	v_max3_f32 v0, v0, v24, v25
	v_max3_f32 v4, v4, v26, v27
	v_cndmask_b32_e64 v88, v177, v11, s[42:43]
	v_cndmask_b32_e64 v91, v177, v12, s[46:47]
	v_max3_f32 v0, v0, v88, v91
	v_cndmask_b32_e64 v90, v177, v13, s[50:51]
	v_cndmask_b32_e64 v85, v177, v14, s[54:55]
	v_max3_f32 v4, v4, v90, v85
	v_add_f32_e32 v15, v142, v15
	v_max3_f32 v0, v0, v60, v61
	v_max3_f32 v4, v4, v62, v63
	v_cndmask_b32_e64 v92, v177, v15, s[58:59]
	v_cndmask_b32_e64 v93, v177, v87, s[62:63]
	v_max3_f32 v0, v0, v92, v93
	v_cndmask_b32_e64 v94, v177, v94, s[66:67]
	v_cndmask_b32_e64 v87, v177, v128, s[70:71]
	v_max3_f32 v4, v4, v94, v87
	v_max_f32_e32 v0, v0, v4
	v_mov_b32_e32 v4, v0
	s_nop 1
	v_permlane32_swap_b32_e32 v0, v4
	v_max_f32_e32 v180, v0, v4
